# v9 plus the six GEMM K-loop heads aligned to 64 bytes
# speedup vs baseline: 1.0125x; 1.0125x over previous
; template <class Epi, class Sched>
; __device__ __forceinline__ void gemm_phase(LAS unsigned char* lds, const Gemm g, const Sched& S, const Epi& E, const int tid) {
;     ...
;         if (E.zero_after(cur))
; #pragma unroll
;         for (int a = 0; a < 2; ++a)
; #pragma unroll
;             for (int b = 0; b < 2; ++b)
; #pragma unroll
;                 for (int m = 0; m < 4; ++m)
; #pragma unroll
;                     for (int n = 0; n < 2; ++n) acc[a][b][m][n] = (f32x4){0.f, 0.f, 0.f, 0.f};
;         cur = nxt; cA = nA; cB = nB; ++ui;
.LBB1_35:
	s_add_u32 s44, s58, 0x100
	v_mov_b32_e32 v2, 0
	s_addc_u32 s45, s59, 0
	s_mov_b32 s71, -2
	v_mov_b32_e32 v3, v2
	v_mov_b32_e32 v4, v2
	v_mov_b32_e32 v5, v2
	v_mov_b32_e32 v6, v2
	v_mov_b32_e32 v7, v2
	v_mov_b32_e32 v8, v2
	v_mov_b32_e32 v9, v2
	v_mov_b32_e32 v18, v2
	v_mov_b32_e32 v19, v2
	v_mov_b32_e32 v20, v2
	v_mov_b32_e32 v21, v2
	v_mov_b32_e32 v22, v2
	v_mov_b32_e32 v23, v2
	v_mov_b32_e32 v24, v2
	v_mov_b32_e32 v25, v2
	v_mov_b32_e32 v34, v2
	v_mov_b32_e32 v35, v2
	v_mov_b32_e32 v36, v2
	v_mov_b32_e32 v37, v2
	v_mov_b32_e32 v38, v2
	v_mov_b32_e32 v39, v2
	v_mov_b32_e32 v40, v2
	v_mov_b32_e32 v41, v2
	v_mov_b32_e32 v50, v2
	v_mov_b32_e32 v51, v2
	v_mov_b32_e32 v52, v2
	v_mov_b32_e32 v53, v2
	v_mov_b32_e32 v54, v2
	v_mov_b32_e32 v55, v2
	v_mov_b32_e32 v56, v2
	v_mov_b32_e32 v57, v2
	v_mov_b32_e32 v10, v2
	v_mov_b32_e32 v11, v2
	v_mov_b32_e32 v12, v2
	v_mov_b32_e32 v13, v2
	v_mov_b32_e32 v14, v2
	v_mov_b32_e32 v15, v2
	v_mov_b32_e32 v16, v2
	v_mov_b32_e32 v17, v2
	v_mov_b32_e32 v26, v2
	v_mov_b32_e32 v27, v2
	v_mov_b32_e32 v28, v2
	v_mov_b32_e32 v29, v2
	v_mov_b32_e32 v30, v2
	v_mov_b32_e32 v31, v2
	v_mov_b32_e32 v32, v2
	v_mov_b32_e32 v33, v2
	v_mov_b32_e32 v42, v2
	v_mov_b32_e32 v43, v2
	v_mov_b32_e32 v44, v2
	v_mov_b32_e32 v45, v2
	v_mov_b32_e32 v46, v2
	v_mov_b32_e32 v47, v2
	v_mov_b32_e32 v48, v2
	v_mov_b32_e32 v49, v2
	v_mov_b32_e32 v58, v2
	v_mov_b32_e32 v59, v2
	v_mov_b32_e32 v60, v2
	v_mov_b32_e32 v61, v2
	v_mov_b32_e32 v62, v2
	v_mov_b32_e32 v63, v2
	v_mov_b32_e32 v64, v2
	v_mov_b32_e32 v65, v2
	v_mov_b32_e32 v66, v2
	v_mov_b32_e32 v67, v2
	v_mov_b32_e32 v68, v2
	v_mov_b32_e32 v69, v2
	v_mov_b32_e32 v70, v2
	v_mov_b32_e32 v71, v2
	v_mov_b32_e32 v72, v2
	v_mov_b32_e32 v73, v2
	v_mov_b32_e32 v82, v2
	v_mov_b32_e32 v83, v2
	v_mov_b32_e32 v84, v2
	v_mov_b32_e32 v85, v2
	v_mov_b32_e32 v86, v2
	v_mov_b32_e32 v87, v2
	v_mov_b32_e32 v88, v2
	v_mov_b32_e32 v89, v2
	v_mov_b32_e32 v98, v2
	v_mov_b32_e32 v99, v2
	v_mov_b32_e32 v100, v2
	v_mov_b32_e32 v101, v2
	v_mov_b32_e32 v102, v2
	v_mov_b32_e32 v103, v2
	v_mov_b32_e32 v104, v2
	v_mov_b32_e32 v105, v2
	v_mov_b32_e32 v114, v2
	v_mov_b32_e32 v115, v2
	v_mov_b32_e32 v116, v2
	v_mov_b32_e32 v117, v2
	v_mov_b32_e32 v118, v2
	v_mov_b32_e32 v119, v2
	v_mov_b32_e32 v120, v2
	v_mov_b32_e32 v121, v2
	v_mov_b32_e32 v74, v2
	v_mov_b32_e32 v75, v2
	v_mov_b32_e32 v76, v2
	v_mov_b32_e32 v77, v2
	v_mov_b32_e32 v78, v2
	v_mov_b32_e32 v79, v2
	v_mov_b32_e32 v80, v2
	v_mov_b32_e32 v81, v2
	v_mov_b32_e32 v90, v2
	v_mov_b32_e32 v91, v2
	v_mov_b32_e32 v92, v2
	v_mov_b32_e32 v93, v2
	v_mov_b32_e32 v94, v2
	v_mov_b32_e32 v95, v2
	v_mov_b32_e32 v96, v2
	v_mov_b32_e32 v97, v2
	v_mov_b32_e32 v106, v2
	v_mov_b32_e32 v107, v2
	v_mov_b32_e32 v108, v2
	v_mov_b32_e32 v109, v2
	v_mov_b32_e32 v110, v2
	v_mov_b32_e32 v111, v2
	v_mov_b32_e32 v112, v2
	v_mov_b32_e32 v113, v2
	v_mov_b32_e32 v122, v2
	v_mov_b32_e32 v123, v2
	v_mov_b32_e32 v124, v2
	v_mov_b32_e32 v125, v2
	v_mov_b32_e32 v126, v2
	v_mov_b32_e32 v127, v2
	v_mov_b32_e32 v128, v2
	v_mov_b32_e32 v129, v2
	.p2align	6

; template <class Epi, class Sched>
; __device__ __forceinline__ void gemm_phase(LAS unsigned char* lds, const Gemm g, const Sched& S, const Epi& E, const int tid) {
;     ...
;         const bool has_next = S.next(ui + 1, nxt);
;         const char* nA = has_next ? (const char*)g.A + (size_t)nxt.pm * tstepA + (size_t)nxt.aoff * 2 : cA; const char* nB = has_next ? (const char*)g.Bt + (size_t)nxt.pn * tstepB : cB;
;         for (int t = 0; t < nt; t += 2) {
;             const bool last = (t == nt - 2);
;             const char* a1 = cA + (size_t)(t + 1) * kstep;
;             const char* a2 = last ? nA : cA + (size_t)(t + 2) * kstep; const char* b2 = last ? nB : cB + (size_t)(t + 2) * kstep;
;             const char* a3 = a2 + kstep; const char* b3 = b2 + kstep;
;     ...
;         if (E.zero_after(cur))
; #pragma unroll
;         for (int a = 0; a < 2; ++a)
; #pragma unroll
;             for (int b = 0; b < 2; ++b)
; #pragma unroll
;                 for (int m = 0; m < 4; ++m)
; #pragma unroll
;                     for (int n = 0; n < 2; ++n) acc[a][b][m][n] = (f32x4){0.f, 0.f, 0.f, 0.f};
;         cur = nxt; cA = nA; cB = nB; ++ui;
.LBB1_86:
	s_ashr_i32 s37, s36, 31
	s_lshl_b64 s[14:15], s[36:37], 20
	s_add_u32 s42, s34, s14
	s_addc_u32 s43, s35, s15
	s_and_b64 s[14:15], s[38:39], exec
	s_cselect_b32 s37, s43, s61
	s_cselect_b32 s53, s42, s60
	s_ashr_i32 s41, s40, 31
	s_lshl_b64 s[14:15], s[40:41], 20
	s_add_u32 s48, s86, s14
	s_addc_u32 s49, s87, s15
	s_and_b64 s[14:15], s[38:39], exec
	s_cselect_b32 s41, s49, s59
	s_cselect_b32 s68, s48, s58
	s_add_u32 s69, s58, 0x100
	s_addc_u32 s44, s59, 0
	s_add_u32 s58, s60, 0x80080
	v_mov_b32_e32 v2, 0
	s_addc_u32 s59, s61, 0
	s_mov_b32 s45, -2
	v_mov_b32_e32 v3, v2
	v_mov_b32_e32 v4, v2
	v_mov_b32_e32 v5, v2
	v_mov_b32_e32 v6, v2
	v_mov_b32_e32 v7, v2
	v_mov_b32_e32 v8, v2
	v_mov_b32_e32 v9, v2
	v_mov_b32_e32 v18, v2
	v_mov_b32_e32 v19, v2
	v_mov_b32_e32 v20, v2
	v_mov_b32_e32 v21, v2
	v_mov_b32_e32 v22, v2
	v_mov_b32_e32 v23, v2
	v_mov_b32_e32 v24, v2
	v_mov_b32_e32 v25, v2
	v_mov_b32_e32 v34, v2
	v_mov_b32_e32 v35, v2
	v_mov_b32_e32 v36, v2
	v_mov_b32_e32 v37, v2
	v_mov_b32_e32 v38, v2
	v_mov_b32_e32 v39, v2
	v_mov_b32_e32 v40, v2
	v_mov_b32_e32 v41, v2
	v_mov_b32_e32 v50, v2
	v_mov_b32_e32 v51, v2
	v_mov_b32_e32 v52, v2
	v_mov_b32_e32 v53, v2
	v_mov_b32_e32 v54, v2
	v_mov_b32_e32 v55, v2
	v_mov_b32_e32 v56, v2
	v_mov_b32_e32 v57, v2
	v_mov_b32_e32 v10, v2
	v_mov_b32_e32 v11, v2
	v_mov_b32_e32 v12, v2
	v_mov_b32_e32 v13, v2
	v_mov_b32_e32 v14, v2
	v_mov_b32_e32 v15, v2
	v_mov_b32_e32 v16, v2
	v_mov_b32_e32 v17, v2
	v_mov_b32_e32 v26, v2
	v_mov_b32_e32 v27, v2
	v_mov_b32_e32 v28, v2
	v_mov_b32_e32 v29, v2
	v_mov_b32_e32 v30, v2
	v_mov_b32_e32 v31, v2
	v_mov_b32_e32 v32, v2
	v_mov_b32_e32 v33, v2
	v_mov_b32_e32 v42, v2
	v_mov_b32_e32 v43, v2
	v_mov_b32_e32 v44, v2
	v_mov_b32_e32 v45, v2
	v_mov_b32_e32 v46, v2
	v_mov_b32_e32 v47, v2
	v_mov_b32_e32 v48, v2
	v_mov_b32_e32 v49, v2
	v_mov_b32_e32 v58, v2
	v_mov_b32_e32 v59, v2
	v_mov_b32_e32 v60, v2
	v_mov_b32_e32 v61, v2
	v_mov_b32_e32 v62, v2
	v_mov_b32_e32 v63, v2
	v_mov_b32_e32 v64, v2
	v_mov_b32_e32 v65, v2
	v_mov_b32_e32 v66, v2
	v_mov_b32_e32 v67, v2
	v_mov_b32_e32 v68, v2
	v_mov_b32_e32 v69, v2
	v_mov_b32_e32 v70, v2
	v_mov_b32_e32 v71, v2
	v_mov_b32_e32 v72, v2
	v_mov_b32_e32 v73, v2
	v_mov_b32_e32 v82, v2
	v_mov_b32_e32 v83, v2
	v_mov_b32_e32 v84, v2
	v_mov_b32_e32 v85, v2
	v_mov_b32_e32 v86, v2
	v_mov_b32_e32 v87, v2
	v_mov_b32_e32 v88, v2
	v_mov_b32_e32 v89, v2
	v_mov_b32_e32 v98, v2
	v_mov_b32_e32 v99, v2
	v_mov_b32_e32 v100, v2
	v_mov_b32_e32 v101, v2
	v_mov_b32_e32 v102, v2
	v_mov_b32_e32 v103, v2
	v_mov_b32_e32 v104, v2
	v_mov_b32_e32 v105, v2
	v_mov_b32_e32 v114, v2
	v_mov_b32_e32 v115, v2
	v_mov_b32_e32 v116, v2
	v_mov_b32_e32 v117, v2
	v_mov_b32_e32 v122, v2
	v_mov_b32_e32 v123, v2
	v_mov_b32_e32 v124, v2
	v_mov_b32_e32 v125, v2
	v_mov_b32_e32 v74, v2
	v_mov_b32_e32 v75, v2
	v_mov_b32_e32 v76, v2
	v_mov_b32_e32 v77, v2
	v_mov_b32_e32 v78, v2
	v_mov_b32_e32 v79, v2
	v_mov_b32_e32 v80, v2
	v_mov_b32_e32 v81, v2
	v_mov_b32_e32 v90, v2
	v_mov_b32_e32 v91, v2
	v_mov_b32_e32 v92, v2
	v_mov_b32_e32 v93, v2
	v_mov_b32_e32 v94, v2
	v_mov_b32_e32 v95, v2
	v_mov_b32_e32 v96, v2
	v_mov_b32_e32 v97, v2
	v_mov_b32_e32 v106, v2
	v_mov_b32_e32 v107, v2
	v_mov_b32_e32 v108, v2
	v_mov_b32_e32 v109, v2
	v_mov_b32_e32 v110, v2
	v_mov_b32_e32 v111, v2
	v_mov_b32_e32 v112, v2
	v_mov_b32_e32 v113, v2
	v_mov_b32_e32 v118, v2
	v_mov_b32_e32 v119, v2
	v_mov_b32_e32 v120, v2
	v_mov_b32_e32 v121, v2
	v_mov_b32_e32 v126, v2
	v_mov_b32_e32 v127, v2
	v_mov_b32_e32 v128, v2
	v_mov_b32_e32 v129, v2
	.p2align	6

; template <class Epi, class Sched>
; __device__ __forceinline__ void gemm_phase(LAS unsigned char* lds, const Gemm g, const Sched& S, const Epi& E, const int tid) {
;     ...
;         const bool has_next = S.next(ui + 1, nxt);
;         const char* nA = has_next ? (const char*)g.A + (size_t)nxt.pm * tstepA + (size_t)nxt.aoff * 2 : cA; const char* nB = has_next ? (const char*)g.Bt + (size_t)nxt.pn * tstepB : cB;
;         for (int t = 0; t < nt; t += 2) {
;             const bool last = (t == nt - 2);
;             const char* a1 = cA + (size_t)(t + 1) * kstep;
;             const char* a2 = last ? nA : cA + (size_t)(t + 2) * kstep; const char* b2 = last ? nB : cB + (size_t)(t + 2) * kstep;
;             const char* a3 = a2 + kstep; const char* b3 = b2 + kstep;
;     ...
;         if (E.zero_after(cur))
; #pragma unroll
;         for (int a = 0; a < 2; ++a)
; #pragma unroll
;             for (int b = 0; b < 2; ++b)
; #pragma unroll
;                 for (int m = 0; m < 4; ++m)
; #pragma unroll
;                     for (int n = 0; n < 2; ++n) acc[a][b][m][n] = (f32x4){0.f, 0.f, 0.f, 0.f};
;         cur = nxt; cA = nA; cB = nB; ++ui;
.LBB1_112:
	s_ashr_i32 s49, s48, 31
	s_lshl_b64 s[14:15], s[48:49], 20
	s_add_u32 s56, s4, s14
	s_addc_u32 s57, s5, s15
	s_and_b64 s[14:15], s[40:41], exec
	s_cselect_b32 s49, s57, s67
	s_cselect_b32 s61, s56, s66
	s_ashr_i32 s53, s52, 31
	s_lshl_b64 s[14:15], s[52:53], 20
	v_readlane_b32 s22, v255, 3
	v_readlane_b32 s23, v255, 4
	s_add_u32 s58, s22, s14
	s_addc_u32 s59, s23, s15
	s_and_b64 s[14:15], s[40:41], exec
	s_cselect_b32 s53, s59, s65
	s_cselect_b32 s74, s58, s64
	s_add_u32 s75, s64, 0x100
	s_addc_u32 s44, s65, 0
	s_add_u32 s64, s66, 0x80080
	v_mov_b32_e32 v2, 0
	s_addc_u32 s65, s67, 0
	s_mov_b32 s45, -2
	v_mov_b32_e32 v3, v2
	v_mov_b32_e32 v4, v2
	v_mov_b32_e32 v5, v2
	v_mov_b32_e32 v6, v2
	v_mov_b32_e32 v7, v2
	v_mov_b32_e32 v8, v2
	v_mov_b32_e32 v9, v2
	v_mov_b32_e32 v18, v2
	v_mov_b32_e32 v19, v2
	v_mov_b32_e32 v20, v2
	v_mov_b32_e32 v21, v2
	v_mov_b32_e32 v22, v2
	v_mov_b32_e32 v23, v2
	v_mov_b32_e32 v24, v2
	v_mov_b32_e32 v25, v2
	v_mov_b32_e32 v34, v2
	v_mov_b32_e32 v35, v2
	v_mov_b32_e32 v36, v2
	v_mov_b32_e32 v37, v2
	v_mov_b32_e32 v38, v2
	v_mov_b32_e32 v39, v2
	v_mov_b32_e32 v40, v2
	v_mov_b32_e32 v41, v2
	v_mov_b32_e32 v50, v2
	v_mov_b32_e32 v51, v2
	v_mov_b32_e32 v52, v2
	v_mov_b32_e32 v53, v2
	v_mov_b32_e32 v54, v2
	v_mov_b32_e32 v55, v2
	v_mov_b32_e32 v56, v2
	v_mov_b32_e32 v57, v2
	v_mov_b32_e32 v10, v2
	v_mov_b32_e32 v11, v2
	v_mov_b32_e32 v12, v2
	v_mov_b32_e32 v13, v2
	v_mov_b32_e32 v14, v2
	v_mov_b32_e32 v15, v2
	v_mov_b32_e32 v16, v2
	v_mov_b32_e32 v17, v2
	v_mov_b32_e32 v26, v2
	v_mov_b32_e32 v27, v2
	v_mov_b32_e32 v28, v2
	v_mov_b32_e32 v29, v2
	v_mov_b32_e32 v30, v2
	v_mov_b32_e32 v31, v2
	v_mov_b32_e32 v32, v2
	v_mov_b32_e32 v33, v2
	v_mov_b32_e32 v42, v2
	v_mov_b32_e32 v43, v2
	v_mov_b32_e32 v44, v2
	v_mov_b32_e32 v45, v2
	v_mov_b32_e32 v46, v2
	v_mov_b32_e32 v47, v2
	v_mov_b32_e32 v48, v2
	v_mov_b32_e32 v49, v2
	v_mov_b32_e32 v58, v2
	v_mov_b32_e32 v59, v2
	v_mov_b32_e32 v60, v2
	v_mov_b32_e32 v61, v2
	v_mov_b32_e32 v62, v2
	v_mov_b32_e32 v63, v2
	v_mov_b32_e32 v64, v2
	v_mov_b32_e32 v65, v2
	v_mov_b32_e32 v66, v2
	v_mov_b32_e32 v67, v2
	v_mov_b32_e32 v68, v2
	v_mov_b32_e32 v69, v2
	v_mov_b32_e32 v70, v2
	v_mov_b32_e32 v71, v2
	v_mov_b32_e32 v72, v2
	v_mov_b32_e32 v73, v2
	v_mov_b32_e32 v82, v2
	v_mov_b32_e32 v83, v2
	v_mov_b32_e32 v84, v2
	v_mov_b32_e32 v85, v2
	v_mov_b32_e32 v86, v2
	v_mov_b32_e32 v87, v2
	v_mov_b32_e32 v88, v2
	v_mov_b32_e32 v89, v2
	v_mov_b32_e32 v98, v2
	v_mov_b32_e32 v99, v2
	v_mov_b32_e32 v100, v2
	v_mov_b32_e32 v101, v2
	v_mov_b32_e32 v102, v2
	v_mov_b32_e32 v103, v2
	v_mov_b32_e32 v104, v2
	v_mov_b32_e32 v105, v2
	v_mov_b32_e32 v114, v2
	v_mov_b32_e32 v115, v2
	v_mov_b32_e32 v116, v2
	v_mov_b32_e32 v117, v2
	v_mov_b32_e32 v118, v2
	v_mov_b32_e32 v119, v2
	v_mov_b32_e32 v120, v2
	v_mov_b32_e32 v121, v2
	v_mov_b32_e32 v74, v2
	v_mov_b32_e32 v75, v2
	v_mov_b32_e32 v76, v2
	v_mov_b32_e32 v77, v2
	v_mov_b32_e32 v78, v2
	v_mov_b32_e32 v79, v2
	v_mov_b32_e32 v80, v2
	v_mov_b32_e32 v81, v2
	v_mov_b32_e32 v90, v2
	v_mov_b32_e32 v91, v2
	v_mov_b32_e32 v92, v2
	v_mov_b32_e32 v93, v2
	v_mov_b32_e32 v94, v2
	v_mov_b32_e32 v95, v2
	v_mov_b32_e32 v96, v2
	v_mov_b32_e32 v97, v2
	v_mov_b32_e32 v106, v2
	v_mov_b32_e32 v107, v2
	v_mov_b32_e32 v108, v2
	v_mov_b32_e32 v109, v2
	v_mov_b32_e32 v110, v2
	v_mov_b32_e32 v111, v2
	v_mov_b32_e32 v112, v2
	v_mov_b32_e32 v113, v2
	v_mov_b32_e32 v122, v2
	v_mov_b32_e32 v123, v2
	v_mov_b32_e32 v124, v2
	v_mov_b32_e32 v125, v2
	v_mov_b32_e32 v126, v2
	v_mov_b32_e32 v127, v2
	v_mov_b32_e32 v128, v2
	v_mov_b32_e32 v129, v2
	.p2align	6

;     __device__ bool next(int j, Unit& u) const {
;         const int i = j / 3, gi = j - 3 * i; Unit t;
;         if (!base.next(i, t)) return false;
;         u.pm = t.pm; u.pn = gi * 8 + t.pn; u.aoff = (gi == 0) ? C_CA : (gi == 1) ? C_OB : C_OC; u.gi = gi; return true;
; template <class Epi, class Sched>
; __device__ __forceinline__ void gemm_phase(LAS unsigned char* lds, const Gemm g, const Sched& S, const Epi& E, const int tid) {
;     ...
;         const bool has_next = S.next(ui + 1, nxt);
;         const char* nA = has_next ? (const char*)g.A + (size_t)nxt.pm * tstepA + (size_t)nxt.aoff * 2 : cA; const char* nB = has_next ? (const char*)g.Bt + (size_t)nxt.pn * tstepB : cB;
;         for (int t = 0; t < nt; t += 2) {
;             const bool last = (t == nt - 2);
;             const char* a1 = cA + (size_t)(t + 1) * kstep;
;             const char* a2 = last ? nA : cA + (size_t)(t + 2) * kstep; const char* b2 = last ? nB : cB + (size_t)(t + 2) * kstep;
;             const char* a3 = a2 + kstep; const char* b3 = b2 + kstep;
.LBB1_155:
	s_ashr_i32 s53, s52, 31
	s_lshl_b64 s[14:15], s[52:53], 19
	v_readlane_b32 s18, v255, 1
	v_readlane_b32 s19, v255, 2
	s_add_u32 s58, s18, s14
	s_addc_u32 s59, s19, s15
	s_and_b64 s[14:15], s[40:41], exec
	s_cselect_b32 s14, s59, s63
	s_cselect_b32 s15, s58, s62
	s_add_u32 s43, s62, 0x100
	s_addc_u32 s44, s63, 0
	s_mov_b32 s45, -2
	.p2align	6

; template <class Epi, class Sched>
; __device__ __forceinline__ void gemm_phase(LAS unsigned char* lds, const Gemm g, const Sched& S, const Epi& E, const int tid) {
;     ...
;         const bool has_next = S.next(ui + 1, nxt);
;         const char* nA = has_next ? (const char*)g.A + (size_t)nxt.pm * tstepA + (size_t)nxt.aoff * 2 : cA; const char* nB = has_next ? (const char*)g.Bt + (size_t)nxt.pn * tstepB : cB;
;         for (int t = 0; t < nt; t += 2) {
;             const bool last = (t == nt - 2);
;             const char* a1 = cA + (size_t)(t + 1) * kstep;
;             const char* a2 = last ? nA : cA + (size_t)(t + 2) * kstep; const char* b2 = last ? nB : cB + (size_t)(t + 2) * kstep;
;             const char* a3 = a2 + kstep; const char* b3 = b2 + kstep;
;     ...
;         if (E.zero_after(cur))
; #pragma unroll
;         for (int a = 0; a < 2; ++a)
; #pragma unroll
;             for (int b = 0; b < 2; ++b)
; #pragma unroll
;                 for (int m = 0; m < 4; ++m)
; #pragma unroll
;                     for (int n = 0; n < 2; ++n) acc[a][b][m][n] = (f32x4){0.f, 0.f, 0.f, 0.f};
;         cur = nxt; cA = nA; cB = nB; ++ui;
.LBB1_573:
	s_ashr_i32 s61, s60, 31
	s_lshl_b64 s[14:15], s[60:61], 20
	s_add_u32 s66, s34, s14
	s_addc_u32 s67, s35, s15
	s_and_b64 s[14:15], s[40:41], exec
	s_cselect_b32 s43, s67, s71
	s_cselect_b32 s47, s66, s70
	s_ashr_i32 s65, s64, 31
	s_lshl_b64 s[14:15], s[64:65], 20
	s_add_u32 s68, s62, s14
	s_addc_u32 s69, s63, s15
	s_and_b64 s[14:15], s[40:41], exec
	s_cselect_b32 s61, s69, s45
	s_cselect_b32 s65, s68, s44
	s_add_u32 s79, s44, 0x100
	s_addc_u32 s80, s45, 0
	s_add_u32 s44, s70, 0x80080
	v_mov_b32_e32 v2, 0
	s_addc_u32 s45, s71, 0
	s_mov_b32 s81, -2
	v_mov_b32_e32 v3, v2
	v_mov_b32_e32 v4, v2
	v_mov_b32_e32 v5, v2
	v_mov_b32_e32 v6, v2
	v_mov_b32_e32 v7, v2
	v_mov_b32_e32 v8, v2
	v_mov_b32_e32 v9, v2
	v_mov_b32_e32 v18, v2
	v_mov_b32_e32 v19, v2
	v_mov_b32_e32 v20, v2
	v_mov_b32_e32 v21, v2
	v_mov_b32_e32 v22, v2
	v_mov_b32_e32 v23, v2
	v_mov_b32_e32 v24, v2
	v_mov_b32_e32 v25, v2
	v_mov_b32_e32 v34, v2
	v_mov_b32_e32 v35, v2
	v_mov_b32_e32 v36, v2
	v_mov_b32_e32 v37, v2
	v_mov_b32_e32 v38, v2
	v_mov_b32_e32 v39, v2
	v_mov_b32_e32 v40, v2
	v_mov_b32_e32 v41, v2
	v_mov_b32_e32 v50, v2
	v_mov_b32_e32 v51, v2
	v_mov_b32_e32 v52, v2
	v_mov_b32_e32 v53, v2
	v_mov_b32_e32 v54, v2
	v_mov_b32_e32 v55, v2
	v_mov_b32_e32 v56, v2
	v_mov_b32_e32 v57, v2
	v_mov_b32_e32 v10, v2
	v_mov_b32_e32 v11, v2
	v_mov_b32_e32 v12, v2
	v_mov_b32_e32 v13, v2
	v_mov_b32_e32 v14, v2
	v_mov_b32_e32 v15, v2
	v_mov_b32_e32 v16, v2
	v_mov_b32_e32 v17, v2
	v_mov_b32_e32 v26, v2
	v_mov_b32_e32 v27, v2
	v_mov_b32_e32 v28, v2
	v_mov_b32_e32 v29, v2
	v_mov_b32_e32 v30, v2
	v_mov_b32_e32 v31, v2
	v_mov_b32_e32 v32, v2
	v_mov_b32_e32 v33, v2
	v_mov_b32_e32 v42, v2
	v_mov_b32_e32 v43, v2
	v_mov_b32_e32 v44, v2
	v_mov_b32_e32 v45, v2
	v_mov_b32_e32 v46, v2
	v_mov_b32_e32 v47, v2
	v_mov_b32_e32 v48, v2
	v_mov_b32_e32 v49, v2
	v_mov_b32_e32 v58, v2
	v_mov_b32_e32 v59, v2
	v_mov_b32_e32 v60, v2
	v_mov_b32_e32 v61, v2
	v_mov_b32_e32 v62, v2
	v_mov_b32_e32 v63, v2
	v_mov_b32_e32 v64, v2
	v_mov_b32_e32 v65, v2
	v_mov_b32_e32 v66, v2
	v_mov_b32_e32 v67, v2
	v_mov_b32_e32 v68, v2
	v_mov_b32_e32 v69, v2
	v_mov_b32_e32 v70, v2
	v_mov_b32_e32 v71, v2
	v_mov_b32_e32 v72, v2
	v_mov_b32_e32 v73, v2
	v_mov_b32_e32 v82, v2
	v_mov_b32_e32 v83, v2
	v_mov_b32_e32 v84, v2
	v_mov_b32_e32 v85, v2
	v_mov_b32_e32 v86, v2
	v_mov_b32_e32 v87, v2
	v_mov_b32_e32 v88, v2
	v_mov_b32_e32 v89, v2
	v_mov_b32_e32 v98, v2
	v_mov_b32_e32 v99, v2
	v_mov_b32_e32 v100, v2
	v_mov_b32_e32 v101, v2
	v_mov_b32_e32 v102, v2
	v_mov_b32_e32 v103, v2
	v_mov_b32_e32 v104, v2
	v_mov_b32_e32 v105, v2
	v_mov_b32_e32 v114, v2
	v_mov_b32_e32 v115, v2
	v_mov_b32_e32 v116, v2
	v_mov_b32_e32 v117, v2
	v_mov_b32_e32 v118, v2
	v_mov_b32_e32 v119, v2
	v_mov_b32_e32 v120, v2
	v_mov_b32_e32 v121, v2
	v_mov_b32_e32 v74, v2
	v_mov_b32_e32 v75, v2
	v_mov_b32_e32 v76, v2
	v_mov_b32_e32 v77, v2
	v_mov_b32_e32 v78, v2
	v_mov_b32_e32 v79, v2
	v_mov_b32_e32 v80, v2
	v_mov_b32_e32 v81, v2
	v_mov_b32_e32 v90, v2
	v_mov_b32_e32 v91, v2
	v_mov_b32_e32 v92, v2
	v_mov_b32_e32 v93, v2
	v_mov_b32_e32 v94, v2
	v_mov_b32_e32 v95, v2
	v_mov_b32_e32 v96, v2
	v_mov_b32_e32 v97, v2
	v_mov_b32_e32 v106, v2
	v_mov_b32_e32 v107, v2
	v_mov_b32_e32 v108, v2
	v_mov_b32_e32 v109, v2
	v_mov_b32_e32 v110, v2
	v_mov_b32_e32 v111, v2
	v_mov_b32_e32 v112, v2
	v_mov_b32_e32 v113, v2
	v_mov_b32_e32 v122, v2
	v_mov_b32_e32 v123, v2
	v_mov_b32_e32 v124, v2
	v_mov_b32_e32 v125, v2
	v_mov_b32_e32 v126, v2
	v_mov_b32_e32 v127, v2
	v_mov_b32_e32 v128, v2
	v_mov_b32_e32 v129, v2
	.p2align	6

; template <class Epi, class Sched>
; __device__ __forceinline__ void gemm_phase(LAS unsigned char* lds, const Gemm g, const Sched& S, const Epi& E, const int tid) {
;     ...
;         const bool has_next = S.next(ui + 1, nxt);
;         const char* nA = has_next ? (const char*)g.A + (size_t)nxt.pm * tstepA + (size_t)nxt.aoff * 2 : cA; const char* nB = has_next ? (const char*)g.Bt + (size_t)nxt.pn * tstepB : cB;
;         for (int t = 0; t < nt; t += 2) {
;             const bool last = (t == nt - 2);
;             const char* a1 = cA + (size_t)(t + 1) * kstep;
;             const char* a2 = last ? nA : cA + (size_t)(t + 2) * kstep; const char* b2 = last ? nB : cB + (size_t)(t + 2) * kstep;
;             const char* a3 = a2 + kstep; const char* b3 = b2 + kstep;
;     ...
;         if (E.zero_after(cur))
; #pragma unroll
;         for (int a = 0; a < 2; ++a)
; #pragma unroll
;             for (int b = 0; b < 2; ++b)
; #pragma unroll
;                 for (int m = 0; m < 4; ++m)
; #pragma unroll
;                     for (int n = 0; n < 2; ++n) acc[a][b][m][n] = (f32x4){0.f, 0.f, 0.f, 0.f};
;         cur = nxt; cA = nA; cB = nB; ++ui;
.LBB1_723:
	s_ashr_i32 s37, s36, 31
	s_lshl_b64 s[14:15], s[36:37], 20
	s_add_u32 s42, s60, s14
	s_addc_u32 s43, s61, s15
	s_and_b64 s[14:15], s[38:39], exec
	s_cselect_b32 s37, s43, s53
	s_cselect_b32 s41, s42, s52
	s_ashr_i32 s27, s26, 31
	s_lshl_b64 s[14:15], s[26:27], 20
	s_add_u32 s44, s34, s14
	s_addc_u32 s45, s35, s15
	s_and_b64 s[14:15], s[38:39], exec
	s_cselect_b32 s27, s45, s49
	s_cselect_b32 s68, s44, s48
	s_add_u32 s69, s48, 0x100
	s_addc_u32 s70, s49, 0
	s_add_u32 s48, s52, 0x80080
	v_mov_b32_e32 v2, 0
	s_addc_u32 s49, s53, 0
	s_mov_b32 s71, -2
	v_mov_b32_e32 v3, v2
	v_mov_b32_e32 v4, v2
	v_mov_b32_e32 v5, v2
	v_mov_b32_e32 v6, v2
	v_mov_b32_e32 v7, v2
	v_mov_b32_e32 v8, v2
	v_mov_b32_e32 v9, v2
	v_mov_b32_e32 v18, v2
	v_mov_b32_e32 v19, v2
	v_mov_b32_e32 v20, v2
	v_mov_b32_e32 v21, v2
	v_mov_b32_e32 v22, v2
	v_mov_b32_e32 v23, v2
	v_mov_b32_e32 v24, v2
	v_mov_b32_e32 v25, v2
	v_mov_b32_e32 v34, v2
	v_mov_b32_e32 v35, v2
	v_mov_b32_e32 v36, v2
	v_mov_b32_e32 v37, v2
	v_mov_b32_e32 v38, v2
	v_mov_b32_e32 v39, v2
	v_mov_b32_e32 v40, v2
	v_mov_b32_e32 v41, v2
	v_mov_b32_e32 v50, v2
	v_mov_b32_e32 v51, v2
	v_mov_b32_e32 v52, v2
	v_mov_b32_e32 v53, v2
	v_mov_b32_e32 v54, v2
	v_mov_b32_e32 v55, v2
	v_mov_b32_e32 v56, v2
	v_mov_b32_e32 v57, v2
	v_mov_b32_e32 v10, v2
	v_mov_b32_e32 v11, v2
	v_mov_b32_e32 v12, v2
	v_mov_b32_e32 v13, v2
	v_mov_b32_e32 v14, v2
	v_mov_b32_e32 v15, v2
	v_mov_b32_e32 v16, v2
	v_mov_b32_e32 v17, v2
	v_mov_b32_e32 v26, v2
	v_mov_b32_e32 v27, v2
	v_mov_b32_e32 v28, v2
	v_mov_b32_e32 v29, v2
	v_mov_b32_e32 v30, v2
	v_mov_b32_e32 v31, v2
	v_mov_b32_e32 v32, v2
	v_mov_b32_e32 v33, v2
	v_mov_b32_e32 v42, v2
	v_mov_b32_e32 v43, v2
	v_mov_b32_e32 v44, v2
	v_mov_b32_e32 v45, v2
	v_mov_b32_e32 v46, v2
	v_mov_b32_e32 v47, v2
	v_mov_b32_e32 v48, v2
	v_mov_b32_e32 v49, v2
	v_mov_b32_e32 v58, v2
	v_mov_b32_e32 v59, v2
	v_mov_b32_e32 v60, v2
	v_mov_b32_e32 v61, v2
	v_mov_b32_e32 v62, v2
	v_mov_b32_e32 v63, v2
	v_mov_b32_e32 v64, v2
	v_mov_b32_e32 v65, v2
	v_mov_b32_e32 v66, v2
	v_mov_b32_e32 v67, v2
	v_mov_b32_e32 v68, v2
	v_mov_b32_e32 v69, v2
	v_mov_b32_e32 v70, v2
	v_mov_b32_e32 v71, v2
	v_mov_b32_e32 v72, v2
	v_mov_b32_e32 v73, v2
	v_mov_b32_e32 v82, v2
	v_mov_b32_e32 v83, v2
	v_mov_b32_e32 v84, v2
	v_mov_b32_e32 v85, v2
	v_mov_b32_e32 v86, v2
	v_mov_b32_e32 v87, v2
	v_mov_b32_e32 v88, v2
	v_mov_b32_e32 v89, v2
	v_mov_b32_e32 v98, v2
	v_mov_b32_e32 v99, v2
	v_mov_b32_e32 v100, v2
	v_mov_b32_e32 v101, v2
	v_mov_b32_e32 v102, v2
	v_mov_b32_e32 v103, v2
	v_mov_b32_e32 v104, v2
	v_mov_b32_e32 v105, v2
	v_mov_b32_e32 v114, v2
	v_mov_b32_e32 v115, v2
	v_mov_b32_e32 v116, v2
	v_mov_b32_e32 v117, v2
	v_mov_b32_e32 v118, v2
	v_mov_b32_e32 v119, v2
	v_mov_b32_e32 v120, v2
	v_mov_b32_e32 v121, v2
	v_mov_b32_e32 v74, v2
	v_mov_b32_e32 v75, v2
	v_mov_b32_e32 v76, v2
	v_mov_b32_e32 v77, v2
	v_mov_b32_e32 v78, v2
	v_mov_b32_e32 v79, v2
	v_mov_b32_e32 v80, v2
	v_mov_b32_e32 v81, v2
	v_mov_b32_e32 v90, v2
	v_mov_b32_e32 v91, v2
	v_mov_b32_e32 v92, v2
	v_mov_b32_e32 v93, v2
	v_mov_b32_e32 v94, v2
	v_mov_b32_e32 v95, v2
	v_mov_b32_e32 v96, v2
	v_mov_b32_e32 v97, v2
	v_mov_b32_e32 v106, v2
	v_mov_b32_e32 v107, v2
	v_mov_b32_e32 v108, v2
	v_mov_b32_e32 v109, v2
	v_mov_b32_e32 v110, v2
	v_mov_b32_e32 v111, v2
	v_mov_b32_e32 v112, v2
	v_mov_b32_e32 v113, v2
	v_mov_b32_e32 v122, v2
	v_mov_b32_e32 v123, v2
	v_mov_b32_e32 v124, v2
	v_mov_b32_e32 v125, v2
	v_mov_b32_e32 v126, v2
	v_mov_b32_e32 v127, v2
	v_mov_b32_e32 v128, v2
	v_mov_b32_e32 v129, v2
	.p2align	6
